# scan-phase tail work (gate low-rank tiles, weight transposes, FFN-in bias rows) on the latent scans' CU-partner workgroups, attention off them
# baseline (speedup 1.0000x reference)
.LBB0_275:
	v_readlane_b32 s12, v227, 0
	s_nop 0
	s_add_i32 s12, s12, 0xffffff00
	s_cmpk_lt_u32 s12, 0xc0
	s_cbranch_scc0 .Lg4_ret
	v_writelane_b32 v224, s12, 43
	s_mov_b32 s2, 1
	v_writelane_b32 v224, s2, 42
	v_readlane_b32 s28, v224, 34
	v_readlane_b32 s29, v224, 35
	v_readlane_b32 s38, v224, 36
	s_mov_b32 s16, 0x1ffffc0
	s_mov_b64 s[52:53], 0x2000
	s_mov_b64 s[40:41], 0x4000
	s_mov_b64 s[42:43], 0x6000
	s_mov_b64 s[56:57], 0x2080
	s_mov_b64 s[58:59], 0x4080
	s_mov_b64 s[72:73], 0x6080
	s_movk_i32 s66, 0x2400
	s_movk_i32 s67, 0x90
	s_waitcnt vmcnt(0) lgkmcnt(0)
	s_barrier
	s_branch .Lg4_entry
.Lg4_ret:
	v_readlane_b32 s58, v224, 36
	v_readlane_b32 s59, v227, 0
	s_movk_i32 s60, 0x3d8
	s_mov_b32 s61, 0
	s_nop 0
	s_cmp_eq_u32 s58, 3
	s_cselect_b32 s60, 0x3c0, s60
	s_add_i32 s59, s59, 0xffffff00
	s_movk_i32 s38, 0x80
	s_cmpk_lt_u32 s59, 0x80
	s_cselect_b32 s59, s59, s60

.Ltr_done:
	s_waitcnt vmcnt(0)
	s_cmp_eq_u32 s61, 0
	s_cbranch_scc0 .Ltr_ret_prep
	s_load_dwordx2 s[56:57], s[100:101], 0x110
	s_load_dwordx2 s[84:85], s[100:101], 0x1b0
	s_load_dwordx2 s[72:73], s[100:101], 0x218
	v_readlane_b32 s59, v227, 0
	v_readfirstlane_b32 s60, v131
	s_nop 0
	s_add_i32 s59, s59, 0xffffff00
	s_cmpk_lt_u32 s59, 0x80
	s_cselect_b32 s59, s59, 0x4000
	s_lshl_b32 s59, s59, 2
	s_lshr_b32 s60, s60, 6
	s_add_i32 s59, s59, s60
	s_movk_i32 s60, 0x1600
	v_and_b32_e32 v2, 63, v131
	v_lshlrev_b32_e32 v3, 6, v2
	v_lshlrev_b32_e32 v2, 5, v2
	v_add_u32_e32 v4, 0x6000, v3
	v_add_u32_e32 v5, 0xc000, v3
	v_add_u32_e32 v6, 0x12000, v3
	v_add_u32_e32 v7, 0x18000, v3
	s_waitcnt lgkmcnt(0)
	s_mul_i32 s20, s58, 0xb00000
	s_add_u32 s56, s56, s20
	s_addc_u32 s57, s57, 0
	s_mul_i32 s20, s58, 0x1e000
	s_add_u32 s84, s84, s20
	s_addc_u32 s85, s85, 0
	s_mul_i32 s20, s58, 0x1b800
	s_add_u32 s72, s72, s20
	s_addc_u32 s73, s73, 0
	s_add_u32 s84, s84, 0x3000
	s_addc_u32 s85, s85, 0
.Lb_loop:
	s_cmp_ge_u32 s59, s60
	s_cbranch_scc1 .Ltr_ret_scan
	s_lshl_b32 s66, s59, 11
	s_add_u32 s2, s56, s66
	s_addc_u32 s3, s57, 0
	s_lshl_b32 s66, s59, 2
	s_add_u32 s64, s72, s66
	s_addc_u32 s65, s73, 0
	global_load_dwordx4 v[10:13], v2, s[2:3]
	global_load_dwordx4 v[14:17], v2, s[2:3] offset:16
	global_load_dwordx4 v[40:43], v3, s[84:85] offset:0
	global_load_dwordx4 v[44:47], v3, s[84:85] offset:16
	global_load_dwordx4 v[48:51], v3, s[84:85] offset:32
	global_load_dwordx4 v[52:55], v3, s[84:85] offset:48
	global_load_dwordx4 v[56:59], v4, s[84:85] offset:0
	global_load_dwordx4 v[60:63], v4, s[84:85] offset:16
	global_load_dwordx4 v[64:67], v4, s[84:85] offset:32
	global_load_dwordx4 v[68:71], v4, s[84:85] offset:48
	global_load_dwordx4 v[72:75], v5, s[84:85] offset:0
	global_load_dwordx4 v[76:79], v5, s[84:85] offset:16
	global_load_dwordx4 v[80:83], v5, s[84:85] offset:32
	global_load_dwordx4 v[84:87], v5, s[84:85] offset:48
	global_load_dwordx4 v[88:91], v6, s[84:85] offset:0
	global_load_dwordx4 v[92:95], v6, s[84:85] offset:16
	global_load_dwordx4 v[96:99], v6, s[84:85] offset:32
	global_load_dwordx4 v[100:103], v6, s[84:85] offset:48
	global_load_dwordx4 v[104:107], v7, s[84:85] offset:0
	global_load_dwordx4 v[108:111], v7, s[84:85] offset:16
	global_load_dwordx4 v[112:115], v7, s[84:85] offset:32
	global_load_dwordx4 v[116:119], v7, s[84:85] offset:48
	s_waitcnt vmcnt(0)
	v_lshrrev_b32_e32 v18, 16, v10
	v_cvt_f32_f16_e32 v20, v10
	v_cvt_f32_f16_e32 v21, v18
	v_lshrrev_b32_e32 v18, 16, v11
	v_cvt_f32_f16_e32 v22, v11
	v_cvt_f32_f16_e32 v23, v18
	v_lshrrev_b32_e32 v18, 16, v12
	v_cvt_f32_f16_e32 v24, v12
	v_cvt_f32_f16_e32 v25, v18
	v_lshrrev_b32_e32 v18, 16, v13
	v_cvt_f32_f16_e32 v26, v13
	v_cvt_f32_f16_e32 v27, v18
	v_lshrrev_b32_e32 v18, 16, v14
	v_cvt_f32_f16_e32 v28, v14
	v_cvt_f32_f16_e32 v29, v18
	v_lshrrev_b32_e32 v18, 16, v15
	v_cvt_f32_f16_e32 v30, v15
	v_cvt_f32_f16_e32 v31, v18
	v_lshrrev_b32_e32 v18, 16, v16
	v_cvt_f32_f16_e32 v32, v16
	v_cvt_f32_f16_e32 v33, v18
	v_lshrrev_b32_e32 v18, 16, v17
	v_cvt_f32_f16_e32 v34, v17
	v_cvt_f32_f16_e32 v35, v18
	v_mul_f32_e32 v120, v40, v20
	v_fmac_f32_e32 v120, v41, v21
	v_fmac_f32_e32 v120, v42, v22
	v_fmac_f32_e32 v120, v43, v23
	v_fmac_f32_e32 v120, v44, v24
	v_fmac_f32_e32 v120, v45, v25
	v_fmac_f32_e32 v120, v46, v26
	v_fmac_f32_e32 v120, v47, v27
	v_fmac_f32_e32 v120, v48, v28
	v_fmac_f32_e32 v120, v49, v29
	v_fmac_f32_e32 v120, v50, v30
	v_fmac_f32_e32 v120, v51, v31
	v_fmac_f32_e32 v120, v52, v32
	v_fmac_f32_e32 v120, v53, v33
	v_fmac_f32_e32 v120, v54, v34
	v_fmac_f32_e32 v120, v55, v35
	v_mul_f32_e32 v121, v56, v20
	v_fmac_f32_e32 v121, v57, v21
	v_fmac_f32_e32 v121, v58, v22
	v_fmac_f32_e32 v121, v59, v23
	v_fmac_f32_e32 v121, v60, v24
	v_fmac_f32_e32 v121, v61, v25
	v_fmac_f32_e32 v121, v62, v26
	v_fmac_f32_e32 v121, v63, v27
	v_fmac_f32_e32 v121, v64, v28
	v_fmac_f32_e32 v121, v65, v29
	v_fmac_f32_e32 v121, v66, v30
	v_fmac_f32_e32 v121, v67, v31
	v_fmac_f32_e32 v121, v68, v32
	v_fmac_f32_e32 v121, v69, v33
	v_fmac_f32_e32 v121, v70, v34
	v_fmac_f32_e32 v121, v71, v35
	v_mul_f32_e32 v122, v72, v20
	v_fmac_f32_e32 v122, v73, v21
	v_fmac_f32_e32 v122, v74, v22
	v_fmac_f32_e32 v122, v75, v23
	v_fmac_f32_e32 v122, v76, v24
	v_fmac_f32_e32 v122, v77, v25
	v_fmac_f32_e32 v122, v78, v26
	v_fmac_f32_e32 v122, v79, v27
	v_fmac_f32_e32 v122, v80, v28
	v_fmac_f32_e32 v122, v81, v29
	v_fmac_f32_e32 v122, v82, v30
	v_fmac_f32_e32 v122, v83, v31
	v_fmac_f32_e32 v122, v84, v32
	v_fmac_f32_e32 v122, v85, v33
	v_fmac_f32_e32 v122, v86, v34
	v_fmac_f32_e32 v122, v87, v35
	v_mul_f32_e32 v123, v88, v20
	v_fmac_f32_e32 v123, v89, v21
	v_fmac_f32_e32 v123, v90, v22
	v_fmac_f32_e32 v123, v91, v23
	v_fmac_f32_e32 v123, v92, v24
	v_fmac_f32_e32 v123, v93, v25
	v_fmac_f32_e32 v123, v94, v26
	v_fmac_f32_e32 v123, v95, v27
	v_fmac_f32_e32 v123, v96, v28
	v_fmac_f32_e32 v123, v97, v29
	v_fmac_f32_e32 v123, v98, v30
	v_fmac_f32_e32 v123, v99, v31
	v_fmac_f32_e32 v123, v100, v32
	v_fmac_f32_e32 v123, v101, v33
	v_fmac_f32_e32 v123, v102, v34
	v_fmac_f32_e32 v123, v103, v35
	v_mul_f32_e32 v124, v104, v20
	v_fmac_f32_e32 v124, v105, v21
	v_fmac_f32_e32 v124, v106, v22
	v_fmac_f32_e32 v124, v107, v23
	v_fmac_f32_e32 v124, v108, v24
	v_fmac_f32_e32 v124, v109, v25
	v_fmac_f32_e32 v124, v110, v26
	v_fmac_f32_e32 v124, v111, v27
	v_fmac_f32_e32 v124, v112, v28
	v_fmac_f32_e32 v124, v113, v29
	v_fmac_f32_e32 v124, v114, v30
	v_fmac_f32_e32 v124, v115, v31
	v_fmac_f32_e32 v124, v116, v32
	v_fmac_f32_e32 v124, v117, v33
	v_fmac_f32_e32 v124, v118, v34
	v_fmac_f32_e32 v124, v119, v35
	s_nop 1
	v_add_f32_dpp v120, v120, v120 quad_perm:[1,0,3,2] row_mask:0xf bank_mask:0xf bound_ctrl:1
	v_add_f32_dpp v121, v121, v121 quad_perm:[1,0,3,2] row_mask:0xf bank_mask:0xf bound_ctrl:1
	v_add_f32_dpp v122, v122, v122 quad_perm:[1,0,3,2] row_mask:0xf bank_mask:0xf bound_ctrl:1
	v_add_f32_dpp v123, v123, v123 quad_perm:[1,0,3,2] row_mask:0xf bank_mask:0xf bound_ctrl:1
	v_add_f32_dpp v124, v124, v124 quad_perm:[1,0,3,2] row_mask:0xf bank_mask:0xf bound_ctrl:1
	s_nop 1
	v_add_f32_dpp v120, v120, v120 quad_perm:[2,3,0,1] row_mask:0xf bank_mask:0xf bound_ctrl:1
	v_add_f32_dpp v121, v121, v121 quad_perm:[2,3,0,1] row_mask:0xf bank_mask:0xf bound_ctrl:1
	v_add_f32_dpp v122, v122, v122 quad_perm:[2,3,0,1] row_mask:0xf bank_mask:0xf bound_ctrl:1
	v_add_f32_dpp v123, v123, v123 quad_perm:[2,3,0,1] row_mask:0xf bank_mask:0xf bound_ctrl:1
	v_add_f32_dpp v124, v124, v124 quad_perm:[2,3,0,1] row_mask:0xf bank_mask:0xf bound_ctrl:1
	s_nop 1
	v_add_f32_dpp v120, v120, v120 row_half_mirror row_mask:0xf bank_mask:0xf bound_ctrl:1
	v_add_f32_dpp v121, v121, v121 row_half_mirror row_mask:0xf bank_mask:0xf bound_ctrl:1
	v_add_f32_dpp v122, v122, v122 row_half_mirror row_mask:0xf bank_mask:0xf bound_ctrl:1
	v_add_f32_dpp v123, v123, v123 row_half_mirror row_mask:0xf bank_mask:0xf bound_ctrl:1
	v_add_f32_dpp v124, v124, v124 row_half_mirror row_mask:0xf bank_mask:0xf bound_ctrl:1
	s_nop 1
	v_add_f32_dpp v120, v120, v120 row_mirror row_mask:0xf bank_mask:0xf bound_ctrl:1
	v_add_f32_dpp v121, v121, v121 row_mirror row_mask:0xf bank_mask:0xf bound_ctrl:1
	v_add_f32_dpp v122, v122, v122 row_mirror row_mask:0xf bank_mask:0xf bound_ctrl:1
	v_add_f32_dpp v123, v123, v123 row_mirror row_mask:0xf bank_mask:0xf bound_ctrl:1
	v_add_f32_dpp v124, v124, v124 row_mirror row_mask:0xf bank_mask:0xf bound_ctrl:1
	s_nop 1
	v_readlane_b32 s66, v120, 0
	v_readlane_b32 s67, v120, 16
	v_readlane_b32 s14, v120, 32
	v_readlane_b32 s15, v120, 48
	s_nop 1
	v_mov_b32_e32 v125, s66
	v_add_f32_e32 v125, s67, v125
	v_add_f32_e32 v125, s14, v125
	v_add_f32_e32 v125, s15, v125
	v_readlane_b32 s66, v121, 0
	v_readlane_b32 s67, v121, 16
	v_readlane_b32 s14, v121, 32
	v_readlane_b32 s15, v121, 48
	s_nop 1
	v_mov_b32_e32 v126, s66
	v_add_f32_e32 v126, s67, v126
	v_add_f32_e32 v126, s14, v126
	v_add_f32_e32 v126, s15, v126
	v_readlane_b32 s66, v122, 0
	v_readlane_b32 s67, v122, 16
	v_readlane_b32 s14, v122, 32
	v_readlane_b32 s15, v122, 48
	s_nop 1
	v_mov_b32_e32 v127, s66
	v_add_f32_e32 v127, s67, v127
	v_add_f32_e32 v127, s14, v127
	v_add_f32_e32 v127, s15, v127
	v_readlane_b32 s66, v123, 0
	v_readlane_b32 s67, v123, 16
	v_readlane_b32 s14, v123, 32
	v_readlane_b32 s15, v123, 48
	s_nop 1
	v_mov_b32_e32 v128, s66
	v_add_f32_e32 v128, s67, v128
	v_add_f32_e32 v128, s14, v128
	v_add_f32_e32 v128, s15, v128
	v_readlane_b32 s66, v124, 0
	v_readlane_b32 s67, v124, 16
	v_readlane_b32 s14, v124, 32
	v_readlane_b32 s15, v124, 48
	s_nop 1
	v_mov_b32_e32 v129, s66
	v_add_f32_e32 v129, s67, v129
	v_add_f32_e32 v129, s14, v129
	v_add_f32_e32 v129, s15, v129
	s_mov_b64 exec, 1
	global_store_dword v1, v125, s[64:65]
	s_add_u32 s64, s64, 0x5800
	s_addc_u32 s65, s65, 0
	global_store_dword v1, v126, s[64:65]
	s_add_u32 s64, s64, 0x5800
	s_addc_u32 s65, s65, 0
	global_store_dword v1, v127, s[64:65]
	s_add_u32 s64, s64, 0x5800
	s_addc_u32 s65, s65, 0
	global_store_dword v1, v128, s[64:65]
	s_add_u32 s64, s64, 0x5800
	s_addc_u32 s65, s65, 0
	global_store_dword v1, v129, s[64:65]
	s_mov_b64 exec, -1
	s_addk_i32 s59, 0x200
	s_branch .Lb_loop
